# grid barrier: the acquire invalidate is issued after the release is observed instead of at arrival (no L2 wipes while other workgroups of the XCD still run the phase)
# baseline (speedup 1.0000x reference)
.LBB0_15:
	buffer_inv sc1
	s_waitcnt vmcnt(0)

.Lxb_wait_0:
	s_mov_b32 s16, 0
